# removed no-op setprio 0/1 pairs between the two MFMA blocks of each GEMM phase
# speedup vs baseline: 1.0391x; 1.0004x over previous
.LBB0_66:
	s_add_u32 s2, s0, 0x4000
	s_addc_u32 s3, s1, 0
	s_cmp_eq_u32 s39, 28
	s_cselect_b32 s22, s25, s2
	s_cselect_b32 s23, s13, s3
	s_cselect_b32 s4, s26, s27
	s_cselect_b32 s5, s15, s38
	s_add_u32 s2, s22, 0x8000
	s_addc_u32 s3, s23, 0
	s_add_i32 s48, 0, 0x10000
	v_add_u32_e32 v0, s48, v141
	s_add_i32 s50, 0, 0x14000
	ds_read_b128 v[150:153], v0
	ds_read_b128 v[154:157], v0 offset:1024
	ds_read_b128 v[158:161], v0 offset:2048
	ds_read_b128 v[162:165], v0 offset:3072
	v_add_u32_e32 v0, s50, v141
	ds_read_b128 v[166:169], v0
	ds_read_b128 v[170:173], v0 offset:1024
	ds_read_b128 v[174:177], v0 offset:2048
	ds_read_b128 v[178:181], v0 offset:3072
	v_lshl_add_u64 v[210:211], s[0:1], 0, v[130:131]
	s_add_i32 m0, s35, 0xc000
	ds_read_b128 v[182:185], v148
	ds_read_b128 v[186:189], v148 offset:1024
	ds_read_b128 v[190:193], v148 offset:2048
	ds_read_b128 v[194:197], v148 offset:3072
	ds_read_b128 v[198:201], v148 offset:4096
	ds_read_b128 v[202:205], v148 offset:5120
	ds_read_b128 v[206:209], v148 offset:6144
	ds_read_b128 v[222:225], v148 offset:7168
	global_load_lds_dwordx4 v[210:211], off
	v_lshl_add_u64 v[210:211], s[0:1], 0, v[132:133]
	s_add_i32 m0, s35, 0xe000
	s_nop 0
	global_load_lds_dwordx4 v[210:211], off
	s_waitcnt vmcnt(8)
	s_waitcnt lgkmcnt(0)
	s_barrier
	s_setprio 1
	s_waitcnt lgkmcnt(0)
	v_mfma_f32_16x16x32_bf16 v[126:129], v[150:153], v[182:185], v[126:129]
	v_mfma_f32_16x16x32_bf16 v[122:125], v[158:161], v[182:185], v[122:125]
	v_mfma_f32_16x16x32_bf16 v[118:121], v[150:153], v[190:193], v[118:121]
	v_mfma_f32_16x16x32_bf16 v[114:117], v[158:161], v[190:193], v[114:117]
	v_mfma_f32_16x16x32_bf16 v[110:113], v[150:153], v[198:201], v[110:113]
	v_mfma_f32_16x16x32_bf16 v[106:109], v[158:161], v[198:201], v[106:109]
	v_mfma_f32_16x16x32_bf16 v[102:105], v[150:153], v[206:209], v[102:105]
	v_mfma_f32_16x16x32_bf16 v[98:101], v[158:161], v[206:209], v[98:101]
	v_mfma_f32_16x16x32_bf16 v[126:129], v[154:157], v[186:189], v[126:129]
	v_mfma_f32_16x16x32_bf16 v[122:125], v[162:165], v[186:189], v[122:125]
	v_mfma_f32_16x16x32_bf16 v[118:121], v[154:157], v[194:197], v[118:121]
	v_mfma_f32_16x16x32_bf16 v[114:117], v[162:165], v[194:197], v[114:117]
	v_mfma_f32_16x16x32_bf16 v[110:113], v[154:157], v[202:205], v[110:113]
	v_mfma_f32_16x16x32_bf16 v[106:109], v[162:165], v[202:205], v[106:109]
	v_mfma_f32_16x16x32_bf16 v[102:105], v[154:157], v[222:225], v[102:105]
	v_mfma_f32_16x16x32_bf16 v[98:101], v[162:165], v[222:225], v[98:101]
	v_mfma_f32_16x16x32_bf16 v[62:65], v[166:169], v[182:185], v[62:65]
	v_mfma_f32_16x16x32_bf16 v[58:61], v[174:177], v[182:185], v[58:61]
	v_mfma_f32_16x16x32_bf16 v[54:57], v[166:169], v[190:193], v[54:57]
	v_mfma_f32_16x16x32_bf16 v[50:53], v[174:177], v[190:193], v[50:53]
	v_mfma_f32_16x16x32_bf16 v[46:49], v[166:169], v[198:201], v[46:49]
	v_mfma_f32_16x16x32_bf16 v[42:45], v[174:177], v[198:201], v[42:45]
	v_mfma_f32_16x16x32_bf16 v[38:41], v[166:169], v[206:209], v[38:41]
	v_mfma_f32_16x16x32_bf16 v[34:37], v[174:177], v[206:209], v[34:37]
	v_mfma_f32_16x16x32_bf16 v[62:65], v[170:173], v[186:189], v[62:65]
	v_mfma_f32_16x16x32_bf16 v[58:61], v[178:181], v[186:189], v[58:61]
	v_mfma_f32_16x16x32_bf16 v[54:57], v[170:173], v[194:197], v[54:57]
	v_mfma_f32_16x16x32_bf16 v[50:53], v[178:181], v[194:197], v[50:53]
	v_mfma_f32_16x16x32_bf16 v[46:49], v[170:173], v[202:205], v[46:49]
	v_mfma_f32_16x16x32_bf16 v[42:45], v[178:181], v[202:205], v[42:45]
	v_mfma_f32_16x16x32_bf16 v[38:41], v[170:173], v[222:225], v[38:41]
	v_mfma_f32_16x16x32_bf16 v[34:37], v[178:181], v[222:225], v[34:37]
	s_setprio 0
	s_barrier
	s_add_i32 s48, s48, s30
	v_lshl_add_u64 v[210:211], s[4:5], 0, v[130:131]
	s_mov_b32 m0, s48
	ds_read_b128 v[182:185], v148 offset:16384
	ds_read_b128 v[186:189], v148 offset:17408
	ds_read_b128 v[190:193], v148 offset:18432
	ds_read_b128 v[194:197], v148 offset:19456
	ds_read_b128 v[198:201], v148 offset:20480
	ds_read_b128 v[202:205], v148 offset:21504
	ds_read_b128 v[206:209], v148 offset:22528
	ds_read_b128 v[222:225], v148 offset:23552
	global_load_lds_dwordx4 v[210:211], off
	s_add_i32 m0, s48, 0x2000
	s_add_u32 s48, s4, 0x4000
	v_lshl_add_u64 v[210:211], s[4:5], 0, v[132:133]
	s_addc_u32 s49, s5, 0
	s_add_i32 s50, s50, s30
	global_load_lds_dwordx4 v[210:211], off
	v_lshl_add_u64 v[210:211], s[48:49], 0, v[130:131]
	s_mov_b32 m0, s50
	s_nop 0
	global_load_lds_dwordx4 v[210:211], off
	v_lshl_add_u64 v[210:211], s[48:49], 0, v[132:133]
	s_add_i32 m0, s50, 0x2000
	s_nop 0
	global_load_lds_dwordx4 v[210:211], off
	v_lshl_add_u64 v[210:211], s[22:23], 0, v[130:131]
	s_mov_b32 m0, s35
	s_nop 0
	global_load_lds_dwordx4 v[210:211], off
	v_lshl_add_u64 v[210:211], s[22:23], 0, v[132:133]
	s_mov_b32 m0, s36
	s_nop 0
	global_load_lds_dwordx4 v[210:211], off
	s_waitcnt vmcnt(8)
	s_waitcnt lgkmcnt(0)
	s_barrier
	s_setprio 1
	s_waitcnt lgkmcnt(0)
	v_mfma_f32_16x16x32_bf16 v[94:97], v[150:153], v[182:185], v[94:97]
	v_mfma_f32_16x16x32_bf16 v[90:93], v[158:161], v[182:185], v[90:93]
	v_mfma_f32_16x16x32_bf16 v[86:89], v[150:153], v[190:193], v[86:89]
	v_mfma_f32_16x16x32_bf16 v[82:85], v[158:161], v[190:193], v[82:85]
	v_mfma_f32_16x16x32_bf16 v[78:81], v[150:153], v[198:201], v[78:81]
	v_mfma_f32_16x16x32_bf16 v[74:77], v[158:161], v[198:201], v[74:77]
	v_mfma_f32_16x16x32_bf16 v[70:73], v[150:153], v[206:209], v[70:73]
	v_mfma_f32_16x16x32_bf16 v[66:69], v[158:161], v[206:209], v[66:69]
	v_mfma_f32_16x16x32_bf16 v[94:97], v[154:157], v[186:189], v[94:97]
	v_mfma_f32_16x16x32_bf16 v[90:93], v[162:165], v[186:189], v[90:93]
	v_mfma_f32_16x16x32_bf16 v[86:89], v[154:157], v[194:197], v[86:89]
	v_mfma_f32_16x16x32_bf16 v[82:85], v[162:165], v[194:197], v[82:85]
	v_mfma_f32_16x16x32_bf16 v[78:81], v[154:157], v[202:205], v[78:81]
	v_mfma_f32_16x16x32_bf16 v[74:77], v[162:165], v[202:205], v[74:77]
	v_mfma_f32_16x16x32_bf16 v[70:73], v[154:157], v[222:225], v[70:73]
	v_mfma_f32_16x16x32_bf16 v[66:69], v[162:165], v[222:225], v[66:69]
	v_mfma_f32_16x16x32_bf16 v[30:33], v[166:169], v[182:185], v[30:33]
	v_mfma_f32_16x16x32_bf16 v[26:29], v[174:177], v[182:185], v[26:29]
	v_mfma_f32_16x16x32_bf16 v[22:25], v[166:169], v[190:193], v[22:25]
	v_mfma_f32_16x16x32_bf16 v[18:21], v[174:177], v[190:193], v[18:21]
	v_mfma_f32_16x16x32_bf16 v[14:17], v[166:169], v[198:201], v[14:17]
	v_mfma_f32_16x16x32_bf16 v[10:13], v[174:177], v[198:201], v[10:13]
	v_mfma_f32_16x16x32_bf16 v[6:9], v[166:169], v[206:209], v[6:9]
	v_mfma_f32_16x16x32_bf16 v[2:5], v[174:177], v[206:209], v[2:5]
	v_mfma_f32_16x16x32_bf16 v[30:33], v[170:173], v[186:189], v[30:33]
	v_mfma_f32_16x16x32_bf16 v[26:29], v[178:181], v[186:189], v[26:29]
	v_mfma_f32_16x16x32_bf16 v[22:25], v[170:173], v[194:197], v[22:25]
	v_mfma_f32_16x16x32_bf16 v[18:21], v[178:181], v[194:197], v[18:21]
	v_mfma_f32_16x16x32_bf16 v[14:17], v[170:173], v[202:205], v[14:17]
	v_mfma_f32_16x16x32_bf16 v[10:13], v[178:181], v[202:205], v[10:13]
	v_mfma_f32_16x16x32_bf16 v[6:9], v[170:173], v[222:225], v[6:9]
	v_mfma_f32_16x16x32_bf16 v[2:5], v[178:181], v[222:225], v[2:5]
	s_setprio 0
	s_barrier
	s_add_i32 s48, 0, 0x18000
	v_add_u32_e32 v0, s48, v141
	s_add_i32 s49, 0, 0x1c000
	ds_read_b128 v[150:153], v0
	ds_read_b128 v[154:157], v0 offset:1024
	ds_read_b128 v[158:161], v0 offset:2048
	ds_read_b128 v[162:165], v0 offset:3072
	v_add_u32_e32 v0, s49, v141
	ds_read_b128 v[166:169], v0
	ds_read_b128 v[170:173], v0 offset:1024
	ds_read_b128 v[174:177], v0 offset:2048
	ds_read_b128 v[178:181], v0 offset:3072
	s_add_u32 s22, s22, 0x4000
	s_addc_u32 s23, s23, 0
	s_mov_b32 m0, s37
	v_lshl_add_u64 v[210:211], s[22:23], 0, v[130:131]
	ds_read_b128 v[182:185], v148 offset:32768
	ds_read_b128 v[186:189], v148 offset:33792
	ds_read_b128 v[190:193], v148 offset:34816
	ds_read_b128 v[194:197], v148 offset:35840
	ds_read_b128 v[198:201], v148 offset:36864
	ds_read_b128 v[202:205], v148 offset:37888
	ds_read_b128 v[206:209], v148 offset:38912
	ds_read_b128 v[222:225], v148 offset:39936
	global_load_lds_dwordx4 v[210:211], off
	v_lshl_add_u64 v[210:211], s[22:23], 0, v[132:133]
	s_mov_b32 m0, s40
	s_nop 0
	global_load_lds_dwordx4 v[210:211], off
	s_waitcnt vmcnt(8)
	s_waitcnt lgkmcnt(0)
	s_barrier
	s_setprio 1
	s_waitcnt lgkmcnt(0)
	v_mfma_f32_16x16x32_bf16 v[126:129], v[150:153], v[182:185], v[126:129]
	v_mfma_f32_16x16x32_bf16 v[122:125], v[158:161], v[182:185], v[122:125]
	v_mfma_f32_16x16x32_bf16 v[118:121], v[150:153], v[190:193], v[118:121]
	v_mfma_f32_16x16x32_bf16 v[114:117], v[158:161], v[190:193], v[114:117]
	v_mfma_f32_16x16x32_bf16 v[110:113], v[150:153], v[198:201], v[110:113]
	v_mfma_f32_16x16x32_bf16 v[106:109], v[158:161], v[198:201], v[106:109]
	v_mfma_f32_16x16x32_bf16 v[102:105], v[150:153], v[206:209], v[102:105]
	v_mfma_f32_16x16x32_bf16 v[98:101], v[158:161], v[206:209], v[98:101]
	v_mfma_f32_16x16x32_bf16 v[126:129], v[154:157], v[186:189], v[126:129]
	v_mfma_f32_16x16x32_bf16 v[122:125], v[162:165], v[186:189], v[122:125]
	v_mfma_f32_16x16x32_bf16 v[118:121], v[154:157], v[194:197], v[118:121]
	v_mfma_f32_16x16x32_bf16 v[114:117], v[162:165], v[194:197], v[114:117]
	v_mfma_f32_16x16x32_bf16 v[110:113], v[154:157], v[202:205], v[110:113]
	v_mfma_f32_16x16x32_bf16 v[106:109], v[162:165], v[202:205], v[106:109]
	v_mfma_f32_16x16x32_bf16 v[102:105], v[154:157], v[222:225], v[102:105]
	v_mfma_f32_16x16x32_bf16 v[98:101], v[162:165], v[222:225], v[98:101]
	v_mfma_f32_16x16x32_bf16 v[62:65], v[166:169], v[182:185], v[62:65]
	v_mfma_f32_16x16x32_bf16 v[58:61], v[174:177], v[182:185], v[58:61]
	v_mfma_f32_16x16x32_bf16 v[54:57], v[166:169], v[190:193], v[54:57]
	v_mfma_f32_16x16x32_bf16 v[50:53], v[174:177], v[190:193], v[50:53]
	v_mfma_f32_16x16x32_bf16 v[46:49], v[166:169], v[198:201], v[46:49]
	v_mfma_f32_16x16x32_bf16 v[42:45], v[174:177], v[198:201], v[42:45]
	v_mfma_f32_16x16x32_bf16 v[38:41], v[166:169], v[206:209], v[38:41]
	v_mfma_f32_16x16x32_bf16 v[34:37], v[174:177], v[206:209], v[34:37]
	v_mfma_f32_16x16x32_bf16 v[62:65], v[170:173], v[186:189], v[62:65]
	v_mfma_f32_16x16x32_bf16 v[58:61], v[178:181], v[186:189], v[58:61]
	v_mfma_f32_16x16x32_bf16 v[54:57], v[170:173], v[194:197], v[54:57]
	v_mfma_f32_16x16x32_bf16 v[50:53], v[178:181], v[194:197], v[50:53]
	v_mfma_f32_16x16x32_bf16 v[46:49], v[170:173], v[202:205], v[46:49]
	v_mfma_f32_16x16x32_bf16 v[42:45], v[178:181], v[202:205], v[42:45]
	v_mfma_f32_16x16x32_bf16 v[38:41], v[170:173], v[222:225], v[38:41]
	v_mfma_f32_16x16x32_bf16 v[34:37], v[178:181], v[222:225], v[34:37]
	s_setprio 0
	s_barrier
	s_add_u32 s22, s4, 0x8000
	s_addc_u32 s23, s5, 0
	s_add_i32 s48, s48, s30
	v_lshl_add_u64 v[210:211], s[22:23], 0, v[130:131]
	s_mov_b32 m0, s48
	ds_read_b128 v[182:185], v148 offset:49152
	ds_read_b128 v[186:189], v148 offset:50176
	ds_read_b128 v[190:193], v148 offset:51200
	ds_read_b128 v[194:197], v148 offset:52224
	ds_read_b128 v[198:201], v148 offset:53248
	ds_read_b128 v[202:205], v148 offset:54272
	ds_read_b128 v[206:209], v148 offset:55296
	ds_read_b128 v[222:225], v148 offset:56320
	global_load_lds_dwordx4 v[210:211], off
	s_add_i32 m0, s48, 0x2000
	s_add_u32 s4, s4, 0xc000
	v_lshl_add_u64 v[210:211], s[22:23], 0, v[132:133]
	s_addc_u32 s5, s5, 0
	s_add_i32 s22, s49, s30
	global_load_lds_dwordx4 v[210:211], off
	v_lshl_add_u64 v[210:211], s[4:5], 0, v[130:131]
	s_mov_b32 m0, s22
	s_nop 0
	global_load_lds_dwordx4 v[210:211], off
	v_lshl_add_u64 v[210:211], s[4:5], 0, v[132:133]
	s_add_i32 m0, s22, 0x2000
	s_nop 0
	global_load_lds_dwordx4 v[210:211], off
	v_lshl_add_u64 v[210:211], s[2:3], 0, v[130:131]
	s_mov_b32 m0, s42
	s_nop 0
	global_load_lds_dwordx4 v[210:211], off
	v_lshl_add_u64 v[210:211], s[2:3], 0, v[132:133]
	s_mov_b32 m0, s43
	s_nop 0
	global_load_lds_dwordx4 v[210:211], off
	s_waitcnt vmcnt(8)
	s_waitcnt lgkmcnt(0)
	s_barrier
	s_setprio 1
	s_waitcnt lgkmcnt(0)
	v_mfma_f32_16x16x32_bf16 v[94:97], v[150:153], v[182:185], v[94:97]
	v_mfma_f32_16x16x32_bf16 v[90:93], v[158:161], v[182:185], v[90:93]
	v_mfma_f32_16x16x32_bf16 v[86:89], v[150:153], v[190:193], v[86:89]
	v_mfma_f32_16x16x32_bf16 v[82:85], v[158:161], v[190:193], v[82:85]
	v_mfma_f32_16x16x32_bf16 v[78:81], v[150:153], v[198:201], v[78:81]
	v_mfma_f32_16x16x32_bf16 v[74:77], v[158:161], v[198:201], v[74:77]
	v_mfma_f32_16x16x32_bf16 v[70:73], v[150:153], v[206:209], v[70:73]
	v_mfma_f32_16x16x32_bf16 v[66:69], v[158:161], v[206:209], v[66:69]
	v_mfma_f32_16x16x32_bf16 v[94:97], v[154:157], v[186:189], v[94:97]
	v_mfma_f32_16x16x32_bf16 v[90:93], v[162:165], v[186:189], v[90:93]
	v_mfma_f32_16x16x32_bf16 v[86:89], v[154:157], v[194:197], v[86:89]
	v_mfma_f32_16x16x32_bf16 v[82:85], v[162:165], v[194:197], v[82:85]
	v_mfma_f32_16x16x32_bf16 v[78:81], v[154:157], v[202:205], v[78:81]
	v_mfma_f32_16x16x32_bf16 v[74:77], v[162:165], v[202:205], v[74:77]
	v_mfma_f32_16x16x32_bf16 v[70:73], v[154:157], v[222:225], v[70:73]
	v_mfma_f32_16x16x32_bf16 v[66:69], v[162:165], v[222:225], v[66:69]
	v_mfma_f32_16x16x32_bf16 v[30:33], v[166:169], v[182:185], v[30:33]
	v_mfma_f32_16x16x32_bf16 v[26:29], v[174:177], v[182:185], v[26:29]
	v_mfma_f32_16x16x32_bf16 v[22:25], v[166:169], v[190:193], v[22:25]
	v_mfma_f32_16x16x32_bf16 v[18:21], v[174:177], v[190:193], v[18:21]
	v_mfma_f32_16x16x32_bf16 v[14:17], v[166:169], v[198:201], v[14:17]
	v_mfma_f32_16x16x32_bf16 v[10:13], v[174:177], v[198:201], v[10:13]
	v_mfma_f32_16x16x32_bf16 v[6:9], v[166:169], v[206:209], v[6:9]
	v_mfma_f32_16x16x32_bf16 v[2:5], v[174:177], v[206:209], v[2:5]
	v_mfma_f32_16x16x32_bf16 v[30:33], v[170:173], v[186:189], v[30:33]
	v_mfma_f32_16x16x32_bf16 v[26:29], v[178:181], v[186:189], v[26:29]
	v_mfma_f32_16x16x32_bf16 v[22:25], v[170:173], v[194:197], v[22:25]
	v_mfma_f32_16x16x32_bf16 v[18:21], v[178:181], v[194:197], v[18:21]
	v_mfma_f32_16x16x32_bf16 v[14:17], v[170:173], v[202:205], v[14:17]
	v_mfma_f32_16x16x32_bf16 v[10:13], v[178:181], v[202:205], v[10:13]
	v_mfma_f32_16x16x32_bf16 v[6:9], v[170:173], v[222:225], v[6:9]
	v_mfma_f32_16x16x32_bf16 v[2:5], v[178:181], v[222:225], v[2:5]
	s_setprio 0
	s_barrier
	s_add_i32 s39, s39, 2
	s_add_u32 s0, s0, 0x10000
	s_addc_u32 s1, s1, 0
	s_add_u32 s27, s27, 0x10000
	s_addc_u32 s38, s38, 0
	s_cmp_gt_u32 s39, 29
	s_cbranch_scc0 .LBB0_66
	s_and_b64 vcc, exec, s[10:11]
	s_cbranch_vccz .LBB0_69
	s_barrier

.LBB0_792:
	s_add_u32 s22, s2, 0x4000
	s_addc_u32 s23, s3, 0
	s_cmp_eq_u32 s57, 12
	s_cselect_b32 s26, s53, s22
	s_cselect_b32 s27, s13, s23
	s_cselect_b32 s24, s54, s55
	s_cselect_b32 s25, s15, s56
	s_add_u32 s22, s26, 0x8000
	s_addc_u32 s23, s27, 0
	s_add_i32 s58, 0, 0x10000
	v_add_u32_e32 v0, s58, v192
	s_add_i32 s60, 0, 0x14000
	ds_read_b128 v[130:133], v0
	ds_read_b128 v[134:137], v0 offset:1024
	ds_read_b128 v[138:141], v0 offset:2048
	ds_read_b128 v[142:145], v0 offset:3072
	v_add_u32_e32 v0, s60, v192
	ds_read_b128 v[146:149], v0
	ds_read_b128 v[150:153], v0 offset:1024
	ds_read_b128 v[154:157], v0 offset:2048
	ds_read_b128 v[158:161], v0 offset:3072
	v_lshl_add_u64 v[204:205], s[2:3], 0, v[178:179]
	s_add_i32 m0, s40, 0xc000
	ds_read_b128 v[162:165], v193
	ds_read_b128 v[166:169], v193 offset:1024
	ds_read_b128 v[170:173], v193 offset:2048
	ds_read_b128 v[174:177], v193 offset:3072
	ds_read_b128 v[182:185], v193 offset:4096
	ds_read_b128 v[186:189], v193 offset:5120
	ds_read_b128 v[196:199], v193 offset:6144
	ds_read_b128 v[200:203], v193 offset:7168
	global_load_lds_dwordx4 v[204:205], off
	v_lshl_add_u64 v[204:205], s[2:3], 0, v[180:181]
	s_add_i32 m0, s40, 0xe000
	s_nop 0
	global_load_lds_dwordx4 v[204:205], off
	s_waitcnt vmcnt(8)
	s_waitcnt lgkmcnt(0)
	s_barrier
	s_setprio 1
	s_waitcnt lgkmcnt(0)
	v_mfma_f32_16x16x32_bf16 v[126:129], v[130:133], v[162:165], v[126:129]
	v_mfma_f32_16x16x32_bf16 v[122:125], v[138:141], v[162:165], v[122:125]
	v_mfma_f32_16x16x32_bf16 v[118:121], v[130:133], v[170:173], v[118:121]
	v_mfma_f32_16x16x32_bf16 v[114:117], v[138:141], v[170:173], v[114:117]
	v_mfma_f32_16x16x32_bf16 v[110:113], v[130:133], v[182:185], v[110:113]
	v_mfma_f32_16x16x32_bf16 v[106:109], v[138:141], v[182:185], v[106:109]
	v_mfma_f32_16x16x32_bf16 v[102:105], v[130:133], v[196:199], v[102:105]
	v_mfma_f32_16x16x32_bf16 v[98:101], v[138:141], v[196:199], v[98:101]
	v_mfma_f32_16x16x32_bf16 v[126:129], v[134:137], v[166:169], v[126:129]
	v_mfma_f32_16x16x32_bf16 v[122:125], v[142:145], v[166:169], v[122:125]
	v_mfma_f32_16x16x32_bf16 v[118:121], v[134:137], v[174:177], v[118:121]
	v_mfma_f32_16x16x32_bf16 v[114:117], v[142:145], v[174:177], v[114:117]
	v_mfma_f32_16x16x32_bf16 v[110:113], v[134:137], v[186:189], v[110:113]
	v_mfma_f32_16x16x32_bf16 v[106:109], v[142:145], v[186:189], v[106:109]
	v_mfma_f32_16x16x32_bf16 v[102:105], v[134:137], v[200:203], v[102:105]
	v_mfma_f32_16x16x32_bf16 v[98:101], v[142:145], v[200:203], v[98:101]
	v_mfma_f32_16x16x32_bf16 v[62:65], v[146:149], v[162:165], v[62:65]
	v_mfma_f32_16x16x32_bf16 v[58:61], v[154:157], v[162:165], v[58:61]
	v_mfma_f32_16x16x32_bf16 v[54:57], v[146:149], v[170:173], v[54:57]
	v_mfma_f32_16x16x32_bf16 v[50:53], v[154:157], v[170:173], v[50:53]
	v_mfma_f32_16x16x32_bf16 v[46:49], v[146:149], v[182:185], v[46:49]
	v_mfma_f32_16x16x32_bf16 v[42:45], v[154:157], v[182:185], v[42:45]
	v_mfma_f32_16x16x32_bf16 v[38:41], v[146:149], v[196:199], v[38:41]
	v_mfma_f32_16x16x32_bf16 v[34:37], v[154:157], v[196:199], v[34:37]
	v_mfma_f32_16x16x32_bf16 v[62:65], v[150:153], v[166:169], v[62:65]
	v_mfma_f32_16x16x32_bf16 v[58:61], v[158:161], v[166:169], v[58:61]
	v_mfma_f32_16x16x32_bf16 v[54:57], v[150:153], v[174:177], v[54:57]
	v_mfma_f32_16x16x32_bf16 v[50:53], v[158:161], v[174:177], v[50:53]
	v_mfma_f32_16x16x32_bf16 v[46:49], v[150:153], v[186:189], v[46:49]
	v_mfma_f32_16x16x32_bf16 v[42:45], v[158:161], v[186:189], v[42:45]
	v_mfma_f32_16x16x32_bf16 v[38:41], v[150:153], v[200:203], v[38:41]
	v_mfma_f32_16x16x32_bf16 v[34:37], v[158:161], v[200:203], v[34:37]
	s_setprio 0
	s_barrier
	s_add_i32 s58, s58, s37
	v_lshl_add_u64 v[204:205], s[24:25], 0, v[178:179]
	s_mov_b32 m0, s58
	ds_read_b128 v[162:165], v193 offset:16384
	ds_read_b128 v[166:169], v193 offset:17408
	ds_read_b128 v[170:173], v193 offset:18432
	ds_read_b128 v[174:177], v193 offset:19456
	ds_read_b128 v[182:185], v193 offset:20480
	ds_read_b128 v[186:189], v193 offset:21504
	ds_read_b128 v[196:199], v193 offset:22528
	ds_read_b128 v[200:203], v193 offset:23552
	global_load_lds_dwordx4 v[204:205], off
	s_add_i32 m0, s58, 0x2000
	s_add_u32 s58, s24, 0x4000
	v_lshl_add_u64 v[204:205], s[24:25], 0, v[180:181]
	s_addc_u32 s59, s25, 0
	s_add_i32 s60, s60, s37
	global_load_lds_dwordx4 v[204:205], off
	v_lshl_add_u64 v[204:205], s[58:59], 0, v[178:179]
	s_mov_b32 m0, s60
	s_nop 0
	global_load_lds_dwordx4 v[204:205], off
	v_lshl_add_u64 v[204:205], s[58:59], 0, v[180:181]
	s_add_i32 m0, s60, 0x2000
	s_nop 0
	global_load_lds_dwordx4 v[204:205], off
	v_lshl_add_u64 v[204:205], s[26:27], 0, v[178:179]
	s_mov_b32 m0, s40
	s_nop 0
	global_load_lds_dwordx4 v[204:205], off
	v_lshl_add_u64 v[204:205], s[26:27], 0, v[180:181]
	s_mov_b32 m0, s41
	s_nop 0
	global_load_lds_dwordx4 v[204:205], off
	s_waitcnt vmcnt(8)
	s_waitcnt lgkmcnt(0)
	s_barrier
	s_setprio 1
	s_waitcnt lgkmcnt(0)
	v_mfma_f32_16x16x32_bf16 v[94:97], v[130:133], v[162:165], v[94:97]
	v_mfma_f32_16x16x32_bf16 v[90:93], v[138:141], v[162:165], v[90:93]
	v_mfma_f32_16x16x32_bf16 v[86:89], v[130:133], v[170:173], v[86:89]
	v_mfma_f32_16x16x32_bf16 v[82:85], v[138:141], v[170:173], v[82:85]
	v_mfma_f32_16x16x32_bf16 v[78:81], v[130:133], v[182:185], v[78:81]
	v_mfma_f32_16x16x32_bf16 v[74:77], v[138:141], v[182:185], v[74:77]
	v_mfma_f32_16x16x32_bf16 v[70:73], v[130:133], v[196:199], v[70:73]
	v_mfma_f32_16x16x32_bf16 v[66:69], v[138:141], v[196:199], v[66:69]
	v_mfma_f32_16x16x32_bf16 v[94:97], v[134:137], v[166:169], v[94:97]
	v_mfma_f32_16x16x32_bf16 v[90:93], v[142:145], v[166:169], v[90:93]
	v_mfma_f32_16x16x32_bf16 v[86:89], v[134:137], v[174:177], v[86:89]
	v_mfma_f32_16x16x32_bf16 v[82:85], v[142:145], v[174:177], v[82:85]
	v_mfma_f32_16x16x32_bf16 v[78:81], v[134:137], v[186:189], v[78:81]
	v_mfma_f32_16x16x32_bf16 v[74:77], v[142:145], v[186:189], v[74:77]
	v_mfma_f32_16x16x32_bf16 v[70:73], v[134:137], v[200:203], v[70:73]
	v_mfma_f32_16x16x32_bf16 v[66:69], v[142:145], v[200:203], v[66:69]
	v_mfma_f32_16x16x32_bf16 v[30:33], v[146:149], v[162:165], v[30:33]
	v_mfma_f32_16x16x32_bf16 v[26:29], v[154:157], v[162:165], v[26:29]
	v_mfma_f32_16x16x32_bf16 v[22:25], v[146:149], v[170:173], v[22:25]
	v_mfma_f32_16x16x32_bf16 v[18:21], v[154:157], v[170:173], v[18:21]
	v_mfma_f32_16x16x32_bf16 v[14:17], v[146:149], v[182:185], v[14:17]
	v_mfma_f32_16x16x32_bf16 v[10:13], v[154:157], v[182:185], v[10:13]
	v_mfma_f32_16x16x32_bf16 v[6:9], v[146:149], v[196:199], v[6:9]
	v_mfma_f32_16x16x32_bf16 v[2:5], v[154:157], v[196:199], v[2:5]
	v_mfma_f32_16x16x32_bf16 v[30:33], v[150:153], v[166:169], v[30:33]
	v_mfma_f32_16x16x32_bf16 v[26:29], v[158:161], v[166:169], v[26:29]
	v_mfma_f32_16x16x32_bf16 v[22:25], v[150:153], v[174:177], v[22:25]
	v_mfma_f32_16x16x32_bf16 v[18:21], v[158:161], v[174:177], v[18:21]
	v_mfma_f32_16x16x32_bf16 v[14:17], v[150:153], v[186:189], v[14:17]
	v_mfma_f32_16x16x32_bf16 v[10:13], v[158:161], v[186:189], v[10:13]
	v_mfma_f32_16x16x32_bf16 v[6:9], v[150:153], v[200:203], v[6:9]
	v_mfma_f32_16x16x32_bf16 v[2:5], v[158:161], v[200:203], v[2:5]
	s_setprio 0
	s_barrier
	s_add_i32 s58, 0, 0x18000
	v_add_u32_e32 v0, s58, v192
	s_add_i32 s59, 0, 0x1c000
	ds_read_b128 v[130:133], v0
	ds_read_b128 v[134:137], v0 offset:1024
	ds_read_b128 v[138:141], v0 offset:2048
	ds_read_b128 v[142:145], v0 offset:3072
	v_add_u32_e32 v0, s59, v192
	ds_read_b128 v[146:149], v0
	ds_read_b128 v[150:153], v0 offset:1024
	ds_read_b128 v[154:157], v0 offset:2048
	ds_read_b128 v[158:161], v0 offset:3072
	s_add_u32 s26, s26, 0x4000
	s_addc_u32 s27, s27, 0
	s_mov_b32 m0, s42
	v_lshl_add_u64 v[204:205], s[26:27], 0, v[178:179]
	ds_read_b128 v[162:165], v193 offset:32768
	ds_read_b128 v[166:169], v193 offset:33792
	ds_read_b128 v[170:173], v193 offset:34816
	ds_read_b128 v[174:177], v193 offset:35840
	ds_read_b128 v[182:185], v193 offset:36864
	ds_read_b128 v[186:189], v193 offset:37888
	ds_read_b128 v[196:199], v193 offset:38912
	ds_read_b128 v[200:203], v193 offset:39936
	global_load_lds_dwordx4 v[204:205], off
	v_lshl_add_u64 v[204:205], s[26:27], 0, v[180:181]
	s_mov_b32 m0, s43
	s_nop 0
	global_load_lds_dwordx4 v[204:205], off
	s_waitcnt vmcnt(8)
	s_waitcnt lgkmcnt(0)
	s_barrier
	s_setprio 1
	s_waitcnt lgkmcnt(0)
	v_mfma_f32_16x16x32_bf16 v[126:129], v[130:133], v[162:165], v[126:129]
	v_mfma_f32_16x16x32_bf16 v[122:125], v[138:141], v[162:165], v[122:125]
	v_mfma_f32_16x16x32_bf16 v[118:121], v[130:133], v[170:173], v[118:121]
	v_mfma_f32_16x16x32_bf16 v[114:117], v[138:141], v[170:173], v[114:117]
	v_mfma_f32_16x16x32_bf16 v[110:113], v[130:133], v[182:185], v[110:113]
	v_mfma_f32_16x16x32_bf16 v[106:109], v[138:141], v[182:185], v[106:109]
	v_mfma_f32_16x16x32_bf16 v[102:105], v[130:133], v[196:199], v[102:105]
	v_mfma_f32_16x16x32_bf16 v[98:101], v[138:141], v[196:199], v[98:101]
	v_mfma_f32_16x16x32_bf16 v[126:129], v[134:137], v[166:169], v[126:129]
	v_mfma_f32_16x16x32_bf16 v[122:125], v[142:145], v[166:169], v[122:125]
	v_mfma_f32_16x16x32_bf16 v[118:121], v[134:137], v[174:177], v[118:121]
	v_mfma_f32_16x16x32_bf16 v[114:117], v[142:145], v[174:177], v[114:117]
	v_mfma_f32_16x16x32_bf16 v[110:113], v[134:137], v[186:189], v[110:113]
	v_mfma_f32_16x16x32_bf16 v[106:109], v[142:145], v[186:189], v[106:109]
	v_mfma_f32_16x16x32_bf16 v[102:105], v[134:137], v[200:203], v[102:105]
	v_mfma_f32_16x16x32_bf16 v[98:101], v[142:145], v[200:203], v[98:101]
	v_mfma_f32_16x16x32_bf16 v[62:65], v[146:149], v[162:165], v[62:65]
	v_mfma_f32_16x16x32_bf16 v[58:61], v[154:157], v[162:165], v[58:61]
	v_mfma_f32_16x16x32_bf16 v[54:57], v[146:149], v[170:173], v[54:57]
	v_mfma_f32_16x16x32_bf16 v[50:53], v[154:157], v[170:173], v[50:53]
	v_mfma_f32_16x16x32_bf16 v[46:49], v[146:149], v[182:185], v[46:49]
	v_mfma_f32_16x16x32_bf16 v[42:45], v[154:157], v[182:185], v[42:45]
	v_mfma_f32_16x16x32_bf16 v[38:41], v[146:149], v[196:199], v[38:41]
	v_mfma_f32_16x16x32_bf16 v[34:37], v[154:157], v[196:199], v[34:37]
	v_mfma_f32_16x16x32_bf16 v[62:65], v[150:153], v[166:169], v[62:65]
	v_mfma_f32_16x16x32_bf16 v[58:61], v[158:161], v[166:169], v[58:61]
	v_mfma_f32_16x16x32_bf16 v[54:57], v[150:153], v[174:177], v[54:57]
	v_mfma_f32_16x16x32_bf16 v[50:53], v[158:161], v[174:177], v[50:53]
	v_mfma_f32_16x16x32_bf16 v[46:49], v[150:153], v[186:189], v[46:49]
	v_mfma_f32_16x16x32_bf16 v[42:45], v[158:161], v[186:189], v[42:45]
	v_mfma_f32_16x16x32_bf16 v[38:41], v[150:153], v[200:203], v[38:41]
	v_mfma_f32_16x16x32_bf16 v[34:37], v[158:161], v[200:203], v[34:37]
	s_setprio 0
	s_barrier
	s_add_u32 s26, s24, 0x8000
	s_addc_u32 s27, s25, 0
	s_add_i32 s58, s58, s37
	v_lshl_add_u64 v[204:205], s[26:27], 0, v[178:179]
	s_mov_b32 m0, s58
	ds_read_b128 v[162:165], v193 offset:49152
	ds_read_b128 v[166:169], v193 offset:50176
	ds_read_b128 v[170:173], v193 offset:51200
	ds_read_b128 v[174:177], v193 offset:52224
	ds_read_b128 v[182:185], v193 offset:53248
	ds_read_b128 v[186:189], v193 offset:54272
	ds_read_b128 v[196:199], v193 offset:55296
	ds_read_b128 v[200:203], v193 offset:56320
	global_load_lds_dwordx4 v[204:205], off
	s_add_i32 m0, s58, 0x2000
	s_add_u32 s24, s24, 0xc000
	v_lshl_add_u64 v[204:205], s[26:27], 0, v[180:181]
	s_addc_u32 s25, s25, 0
	s_add_i32 s26, s59, s37
	global_load_lds_dwordx4 v[204:205], off
	v_lshl_add_u64 v[204:205], s[24:25], 0, v[178:179]
	s_mov_b32 m0, s26
	s_nop 0
	global_load_lds_dwordx4 v[204:205], off
	v_lshl_add_u64 v[204:205], s[24:25], 0, v[180:181]
	s_add_i32 m0, s26, 0x2000
	s_nop 0
	global_load_lds_dwordx4 v[204:205], off
	v_lshl_add_u64 v[204:205], s[22:23], 0, v[178:179]
	s_mov_b32 m0, s47
	s_nop 0
	global_load_lds_dwordx4 v[204:205], off
	v_lshl_add_u64 v[204:205], s[22:23], 0, v[180:181]
	s_mov_b32 m0, s48
	s_nop 0
	global_load_lds_dwordx4 v[204:205], off
	s_waitcnt vmcnt(8)
	s_waitcnt lgkmcnt(0)
	s_barrier
	s_setprio 1
	s_waitcnt lgkmcnt(0)
	v_mfma_f32_16x16x32_bf16 v[94:97], v[130:133], v[162:165], v[94:97]
	v_mfma_f32_16x16x32_bf16 v[90:93], v[138:141], v[162:165], v[90:93]
	v_mfma_f32_16x16x32_bf16 v[86:89], v[130:133], v[170:173], v[86:89]
	v_mfma_f32_16x16x32_bf16 v[82:85], v[138:141], v[170:173], v[82:85]
	v_mfma_f32_16x16x32_bf16 v[78:81], v[130:133], v[182:185], v[78:81]
	v_mfma_f32_16x16x32_bf16 v[74:77], v[138:141], v[182:185], v[74:77]
	v_mfma_f32_16x16x32_bf16 v[70:73], v[130:133], v[196:199], v[70:73]
	v_mfma_f32_16x16x32_bf16 v[66:69], v[138:141], v[196:199], v[66:69]
	v_mfma_f32_16x16x32_bf16 v[94:97], v[134:137], v[166:169], v[94:97]
	v_mfma_f32_16x16x32_bf16 v[90:93], v[142:145], v[166:169], v[90:93]
	v_mfma_f32_16x16x32_bf16 v[86:89], v[134:137], v[174:177], v[86:89]
	v_mfma_f32_16x16x32_bf16 v[82:85], v[142:145], v[174:177], v[82:85]
	v_mfma_f32_16x16x32_bf16 v[78:81], v[134:137], v[186:189], v[78:81]
	v_mfma_f32_16x16x32_bf16 v[74:77], v[142:145], v[186:189], v[74:77]
	v_mfma_f32_16x16x32_bf16 v[70:73], v[134:137], v[200:203], v[70:73]
	v_mfma_f32_16x16x32_bf16 v[66:69], v[142:145], v[200:203], v[66:69]
	v_mfma_f32_16x16x32_bf16 v[30:33], v[146:149], v[162:165], v[30:33]
	v_mfma_f32_16x16x32_bf16 v[26:29], v[154:157], v[162:165], v[26:29]
	v_mfma_f32_16x16x32_bf16 v[22:25], v[146:149], v[170:173], v[22:25]
	v_mfma_f32_16x16x32_bf16 v[18:21], v[154:157], v[170:173], v[18:21]
	v_mfma_f32_16x16x32_bf16 v[14:17], v[146:149], v[182:185], v[14:17]
	v_mfma_f32_16x16x32_bf16 v[10:13], v[154:157], v[182:185], v[10:13]
	v_mfma_f32_16x16x32_bf16 v[6:9], v[146:149], v[196:199], v[6:9]
	v_mfma_f32_16x16x32_bf16 v[2:5], v[154:157], v[196:199], v[2:5]
	v_mfma_f32_16x16x32_bf16 v[30:33], v[150:153], v[166:169], v[30:33]
	v_mfma_f32_16x16x32_bf16 v[26:29], v[158:161], v[166:169], v[26:29]
	v_mfma_f32_16x16x32_bf16 v[22:25], v[150:153], v[174:177], v[22:25]
	v_mfma_f32_16x16x32_bf16 v[18:21], v[158:161], v[174:177], v[18:21]
	v_mfma_f32_16x16x32_bf16 v[14:17], v[150:153], v[186:189], v[14:17]
	v_mfma_f32_16x16x32_bf16 v[10:13], v[158:161], v[186:189], v[10:13]
	v_mfma_f32_16x16x32_bf16 v[6:9], v[150:153], v[200:203], v[6:9]
	v_mfma_f32_16x16x32_bf16 v[2:5], v[158:161], v[200:203], v[2:5]
	s_setprio 0
	s_barrier
	s_add_i32 s57, s57, 2
	s_add_u32 s2, s2, 0x10000
	s_addc_u32 s3, s3, 0
	s_add_u32 s55, s55, 0x10000
	s_addc_u32 s56, s56, 0
	s_cmp_gt_u32 s57, 13
	s_cbranch_scc0 .LBB0_792
	s_and_b64 vcc, exec, s[8:9]
	s_cbranch_vccz .LBB0_795
	s_barrier

.LBB0_932:
	s_add_u32 s2, s0, 0x4000
	s_addc_u32 s3, s1, 0
	s_cmp_eq_u32 s47, 28
	s_cselect_b32 s24, s43, s2
	s_cselect_b32 s25, s13, s3
	s_cselect_b32 s22, s44, s45
	s_cselect_b32 s23, s15, s46
	s_add_u32 s2, s24, 0x8000
	s_addc_u32 s3, s25, 0
	s_add_i32 s48, 0, 0x10000
	s_add_i32 s50, 0, 0x14000
	v_add_u32_e32 v142, s48, v179
	v_add_u32_e32 v158, s50, v179
	ds_read_b128 v[130:133], v142
	ds_read_b128 v[134:137], v142 offset:1024
	ds_read_b128 v[138:141], v142 offset:2048
	ds_read_b128 v[142:145], v142 offset:3072
	ds_read_b128 v[146:149], v158
	ds_read_b128 v[150:153], v158 offset:1024
	ds_read_b128 v[154:157], v158 offset:2048
	ds_read_b128 v[158:161], v158 offset:3072
	v_lshl_add_u64 v[176:177], s[0:1], 0, v[0:1]
	s_add_i32 m0, s30, 0xc000
	ds_read_b128 v[168:171], v180
	ds_read_b128 v[172:175], v180 offset:1024
	ds_read_b128 v[182:185], v180 offset:2048
	ds_read_b128 v[186:189], v180 offset:3072
	ds_read_b128 v[190:193], v180 offset:4096
	ds_read_b128 v[194:197], v180 offset:5120
	ds_read_b128 v[198:201], v180 offset:6144
	ds_read_b128 v[202:205], v180 offset:7168
	global_load_lds_dwordx4 v[176:177], off
	v_lshl_add_u64 v[176:177], s[0:1], 0, v[162:163]
	s_add_i32 m0, s30, 0xe000
	s_nop 0
	global_load_lds_dwordx4 v[176:177], off
	s_waitcnt vmcnt(8)
	s_waitcnt lgkmcnt(0)
	s_barrier
	s_setprio 1
	s_waitcnt lgkmcnt(0)
	v_mfma_f32_16x16x32_bf16 v[126:129], v[130:133], v[168:171], v[126:129]
	v_mfma_f32_16x16x32_bf16 v[122:125], v[138:141], v[168:171], v[122:125]
	v_mfma_f32_16x16x32_bf16 v[118:121], v[130:133], v[182:185], v[118:121]
	v_mfma_f32_16x16x32_bf16 v[114:117], v[138:141], v[182:185], v[114:117]
	v_mfma_f32_16x16x32_bf16 v[110:113], v[130:133], v[190:193], v[110:113]
	v_mfma_f32_16x16x32_bf16 v[106:109], v[138:141], v[190:193], v[106:109]
	v_mfma_f32_16x16x32_bf16 v[102:105], v[130:133], v[198:201], v[102:105]
	v_mfma_f32_16x16x32_bf16 v[98:101], v[138:141], v[198:201], v[98:101]
	v_mfma_f32_16x16x32_bf16 v[126:129], v[134:137], v[172:175], v[126:129]
	v_mfma_f32_16x16x32_bf16 v[122:125], v[142:145], v[172:175], v[122:125]
	v_mfma_f32_16x16x32_bf16 v[118:121], v[134:137], v[186:189], v[118:121]
	v_mfma_f32_16x16x32_bf16 v[114:117], v[142:145], v[186:189], v[114:117]
	v_mfma_f32_16x16x32_bf16 v[110:113], v[134:137], v[194:197], v[110:113]
	v_mfma_f32_16x16x32_bf16 v[106:109], v[142:145], v[194:197], v[106:109]
	v_mfma_f32_16x16x32_bf16 v[102:105], v[134:137], v[202:205], v[102:105]
	v_mfma_f32_16x16x32_bf16 v[98:101], v[142:145], v[202:205], v[98:101]
	v_mfma_f32_16x16x32_bf16 v[62:65], v[146:149], v[168:171], v[62:65]
	v_mfma_f32_16x16x32_bf16 v[58:61], v[154:157], v[168:171], v[58:61]
	v_mfma_f32_16x16x32_bf16 v[54:57], v[146:149], v[182:185], v[54:57]
	v_mfma_f32_16x16x32_bf16 v[50:53], v[154:157], v[182:185], v[50:53]
	v_mfma_f32_16x16x32_bf16 v[46:49], v[146:149], v[190:193], v[46:49]
	v_mfma_f32_16x16x32_bf16 v[42:45], v[154:157], v[190:193], v[42:45]
	v_mfma_f32_16x16x32_bf16 v[38:41], v[146:149], v[198:201], v[38:41]
	v_mfma_f32_16x16x32_bf16 v[34:37], v[154:157], v[198:201], v[34:37]
	v_mfma_f32_16x16x32_bf16 v[62:65], v[150:153], v[172:175], v[62:65]
	v_mfma_f32_16x16x32_bf16 v[58:61], v[158:161], v[172:175], v[58:61]
	v_mfma_f32_16x16x32_bf16 v[54:57], v[150:153], v[186:189], v[54:57]
	v_mfma_f32_16x16x32_bf16 v[50:53], v[158:161], v[186:189], v[50:53]
	v_mfma_f32_16x16x32_bf16 v[46:49], v[150:153], v[194:197], v[46:49]
	v_mfma_f32_16x16x32_bf16 v[42:45], v[158:161], v[194:197], v[42:45]
	v_mfma_f32_16x16x32_bf16 v[38:41], v[150:153], v[202:205], v[38:41]
	v_mfma_f32_16x16x32_bf16 v[34:37], v[158:161], v[202:205], v[34:37]
	s_setprio 0
	s_barrier
	s_add_i32 s48, s48, s29
	v_lshl_add_u64 v[176:177], s[22:23], 0, v[0:1]
	s_mov_b32 m0, s48
	ds_read_b128 v[168:171], v180 offset:16384
	ds_read_b128 v[172:175], v180 offset:17408
	ds_read_b128 v[182:185], v180 offset:18432
	ds_read_b128 v[186:189], v180 offset:19456
	ds_read_b128 v[190:193], v180 offset:20480
	ds_read_b128 v[194:197], v180 offset:21504
	ds_read_b128 v[198:201], v180 offset:22528
	ds_read_b128 v[202:205], v180 offset:23552
	global_load_lds_dwordx4 v[176:177], off
	s_add_i32 m0, s48, 0x2000
	s_add_u32 s48, s22, 0x4000
	v_lshl_add_u64 v[176:177], s[22:23], 0, v[162:163]
	s_addc_u32 s49, s23, 0
	s_add_i32 s50, s50, s29
	global_load_lds_dwordx4 v[176:177], off
	v_lshl_add_u64 v[176:177], s[48:49], 0, v[0:1]
	s_mov_b32 m0, s50
	s_nop 0
	global_load_lds_dwordx4 v[176:177], off
	v_lshl_add_u64 v[176:177], s[48:49], 0, v[162:163]
	s_add_i32 m0, s50, 0x2000
	s_nop 0
	global_load_lds_dwordx4 v[176:177], off
	v_lshl_add_u64 v[176:177], s[24:25], 0, v[0:1]
	s_mov_b32 m0, s30
	s_nop 0
	global_load_lds_dwordx4 v[176:177], off
	v_lshl_add_u64 v[176:177], s[24:25], 0, v[162:163]
	s_mov_b32 m0, s31
	s_nop 0
	global_load_lds_dwordx4 v[176:177], off
	s_waitcnt vmcnt(8)
	s_waitcnt lgkmcnt(0)
	s_barrier
	s_setprio 1
	s_waitcnt lgkmcnt(0)
	v_mfma_f32_16x16x32_bf16 v[94:97], v[130:133], v[168:171], v[94:97]
	v_mfma_f32_16x16x32_bf16 v[90:93], v[138:141], v[168:171], v[90:93]
	v_mfma_f32_16x16x32_bf16 v[86:89], v[130:133], v[182:185], v[86:89]
	v_mfma_f32_16x16x32_bf16 v[82:85], v[138:141], v[182:185], v[82:85]
	v_mfma_f32_16x16x32_bf16 v[78:81], v[130:133], v[190:193], v[78:81]
	v_mfma_f32_16x16x32_bf16 v[74:77], v[138:141], v[190:193], v[74:77]
	v_mfma_f32_16x16x32_bf16 v[70:73], v[130:133], v[198:201], v[70:73]
	v_mfma_f32_16x16x32_bf16 v[66:69], v[138:141], v[198:201], v[66:69]
	v_mfma_f32_16x16x32_bf16 v[94:97], v[134:137], v[172:175], v[94:97]
	v_mfma_f32_16x16x32_bf16 v[90:93], v[142:145], v[172:175], v[90:93]
	v_mfma_f32_16x16x32_bf16 v[86:89], v[134:137], v[186:189], v[86:89]
	v_mfma_f32_16x16x32_bf16 v[82:85], v[142:145], v[186:189], v[82:85]
	v_mfma_f32_16x16x32_bf16 v[78:81], v[134:137], v[194:197], v[78:81]
	v_mfma_f32_16x16x32_bf16 v[74:77], v[142:145], v[194:197], v[74:77]
	v_mfma_f32_16x16x32_bf16 v[70:73], v[134:137], v[202:205], v[70:73]
	v_mfma_f32_16x16x32_bf16 v[66:69], v[142:145], v[202:205], v[66:69]
	v_mfma_f32_16x16x32_bf16 v[30:33], v[146:149], v[168:171], v[30:33]
	v_mfma_f32_16x16x32_bf16 v[26:29], v[154:157], v[168:171], v[26:29]
	v_mfma_f32_16x16x32_bf16 v[22:25], v[146:149], v[182:185], v[22:25]
	v_mfma_f32_16x16x32_bf16 v[18:21], v[154:157], v[182:185], v[18:21]
	v_mfma_f32_16x16x32_bf16 v[14:17], v[146:149], v[190:193], v[14:17]
	v_mfma_f32_16x16x32_bf16 v[10:13], v[154:157], v[190:193], v[10:13]
	v_mfma_f32_16x16x32_bf16 v[6:9], v[146:149], v[198:201], v[6:9]
	v_mfma_f32_16x16x32_bf16 v[2:5], v[154:157], v[198:201], v[2:5]
	v_mfma_f32_16x16x32_bf16 v[30:33], v[150:153], v[172:175], v[30:33]
	v_mfma_f32_16x16x32_bf16 v[26:29], v[158:161], v[172:175], v[26:29]
	v_mfma_f32_16x16x32_bf16 v[22:25], v[150:153], v[186:189], v[22:25]
	v_mfma_f32_16x16x32_bf16 v[18:21], v[158:161], v[186:189], v[18:21]
	v_mfma_f32_16x16x32_bf16 v[14:17], v[150:153], v[194:197], v[14:17]
	v_mfma_f32_16x16x32_bf16 v[10:13], v[158:161], v[194:197], v[10:13]
	v_mfma_f32_16x16x32_bf16 v[6:9], v[150:153], v[202:205], v[6:9]
	v_mfma_f32_16x16x32_bf16 v[2:5], v[158:161], v[202:205], v[2:5]
	s_setprio 0
	s_barrier
	s_add_i32 s48, 0, 0x18000
	s_add_i32 s49, 0, 0x1c000
	v_add_u32_e32 v142, s48, v179
	v_add_u32_e32 v158, s49, v179
	ds_read_b128 v[130:133], v142
	ds_read_b128 v[134:137], v142 offset:1024
	ds_read_b128 v[138:141], v142 offset:2048
	ds_read_b128 v[142:145], v142 offset:3072
	ds_read_b128 v[146:149], v158
	ds_read_b128 v[150:153], v158 offset:1024
	ds_read_b128 v[154:157], v158 offset:2048
	ds_read_b128 v[158:161], v158 offset:3072
	s_add_u32 s24, s24, 0x4000
	s_addc_u32 s25, s25, 0
	s_mov_b32 m0, s34
	v_lshl_add_u64 v[176:177], s[24:25], 0, v[0:1]
	ds_read_b128 v[168:171], v180 offset:32768
	ds_read_b128 v[172:175], v180 offset:33792
	ds_read_b128 v[182:185], v180 offset:34816
	ds_read_b128 v[186:189], v180 offset:35840
	ds_read_b128 v[190:193], v180 offset:36864
	ds_read_b128 v[194:197], v180 offset:37888
	ds_read_b128 v[198:201], v180 offset:38912
	ds_read_b128 v[202:205], v180 offset:39936
	global_load_lds_dwordx4 v[176:177], off
	v_lshl_add_u64 v[176:177], s[24:25], 0, v[162:163]
	s_mov_b32 m0, s35
	s_nop 0
	global_load_lds_dwordx4 v[176:177], off
	s_waitcnt vmcnt(8)
	s_waitcnt lgkmcnt(0)
	s_barrier
	s_setprio 1
	s_waitcnt lgkmcnt(0)
	v_mfma_f32_16x16x32_bf16 v[126:129], v[130:133], v[168:171], v[126:129]
	v_mfma_f32_16x16x32_bf16 v[122:125], v[138:141], v[168:171], v[122:125]
	v_mfma_f32_16x16x32_bf16 v[118:121], v[130:133], v[182:185], v[118:121]
	v_mfma_f32_16x16x32_bf16 v[114:117], v[138:141], v[182:185], v[114:117]
	v_mfma_f32_16x16x32_bf16 v[110:113], v[130:133], v[190:193], v[110:113]
	v_mfma_f32_16x16x32_bf16 v[106:109], v[138:141], v[190:193], v[106:109]
	v_mfma_f32_16x16x32_bf16 v[102:105], v[130:133], v[198:201], v[102:105]
	v_mfma_f32_16x16x32_bf16 v[98:101], v[138:141], v[198:201], v[98:101]
	v_mfma_f32_16x16x32_bf16 v[126:129], v[134:137], v[172:175], v[126:129]
	v_mfma_f32_16x16x32_bf16 v[122:125], v[142:145], v[172:175], v[122:125]
	v_mfma_f32_16x16x32_bf16 v[118:121], v[134:137], v[186:189], v[118:121]
	v_mfma_f32_16x16x32_bf16 v[114:117], v[142:145], v[186:189], v[114:117]
	v_mfma_f32_16x16x32_bf16 v[110:113], v[134:137], v[194:197], v[110:113]
	v_mfma_f32_16x16x32_bf16 v[106:109], v[142:145], v[194:197], v[106:109]
	v_mfma_f32_16x16x32_bf16 v[102:105], v[134:137], v[202:205], v[102:105]
	v_mfma_f32_16x16x32_bf16 v[98:101], v[142:145], v[202:205], v[98:101]
	v_mfma_f32_16x16x32_bf16 v[62:65], v[146:149], v[168:171], v[62:65]
	v_mfma_f32_16x16x32_bf16 v[58:61], v[154:157], v[168:171], v[58:61]
	v_mfma_f32_16x16x32_bf16 v[54:57], v[146:149], v[182:185], v[54:57]
	v_mfma_f32_16x16x32_bf16 v[50:53], v[154:157], v[182:185], v[50:53]
	v_mfma_f32_16x16x32_bf16 v[46:49], v[146:149], v[190:193], v[46:49]
	v_mfma_f32_16x16x32_bf16 v[42:45], v[154:157], v[190:193], v[42:45]
	v_mfma_f32_16x16x32_bf16 v[38:41], v[146:149], v[198:201], v[38:41]
	v_mfma_f32_16x16x32_bf16 v[34:37], v[154:157], v[198:201], v[34:37]
	v_mfma_f32_16x16x32_bf16 v[62:65], v[150:153], v[172:175], v[62:65]
	v_mfma_f32_16x16x32_bf16 v[58:61], v[158:161], v[172:175], v[58:61]
	v_mfma_f32_16x16x32_bf16 v[54:57], v[150:153], v[186:189], v[54:57]
	v_mfma_f32_16x16x32_bf16 v[50:53], v[158:161], v[186:189], v[50:53]
	v_mfma_f32_16x16x32_bf16 v[46:49], v[150:153], v[194:197], v[46:49]
	v_mfma_f32_16x16x32_bf16 v[42:45], v[158:161], v[194:197], v[42:45]
	v_mfma_f32_16x16x32_bf16 v[38:41], v[150:153], v[202:205], v[38:41]
	v_mfma_f32_16x16x32_bf16 v[34:37], v[158:161], v[202:205], v[34:37]
	s_setprio 0
	s_barrier
	s_add_u32 s24, s22, 0x8000
	s_addc_u32 s25, s23, 0
	s_add_i32 s48, s48, s29
	v_lshl_add_u64 v[176:177], s[24:25], 0, v[0:1]
	s_mov_b32 m0, s48
	ds_read_b128 v[168:171], v180 offset:49152
	ds_read_b128 v[172:175], v180 offset:50176
	ds_read_b128 v[182:185], v180 offset:51200
	ds_read_b128 v[186:189], v180 offset:52224
	ds_read_b128 v[190:193], v180 offset:53248
	ds_read_b128 v[194:197], v180 offset:54272
	ds_read_b128 v[198:201], v180 offset:55296
	ds_read_b128 v[202:205], v180 offset:56320
	global_load_lds_dwordx4 v[176:177], off
	s_add_i32 m0, s48, 0x2000
	s_add_u32 s22, s22, 0xc000
	v_lshl_add_u64 v[176:177], s[24:25], 0, v[162:163]
	s_addc_u32 s23, s23, 0
	s_add_i32 s24, s49, s29
	global_load_lds_dwordx4 v[176:177], off
	v_lshl_add_u64 v[176:177], s[22:23], 0, v[0:1]
	s_mov_b32 m0, s24
	s_nop 0
	global_load_lds_dwordx4 v[176:177], off
	v_lshl_add_u64 v[176:177], s[22:23], 0, v[162:163]
	s_add_i32 m0, s24, 0x2000
	s_nop 0
	global_load_lds_dwordx4 v[176:177], off
	v_lshl_add_u64 v[176:177], s[2:3], 0, v[0:1]
	s_mov_b32 m0, s38
	s_nop 0
	global_load_lds_dwordx4 v[176:177], off
	v_lshl_add_u64 v[176:177], s[2:3], 0, v[162:163]
	s_mov_b32 m0, s39
	s_nop 0
	global_load_lds_dwordx4 v[176:177], off
	s_waitcnt vmcnt(8)
	s_waitcnt lgkmcnt(0)
	s_barrier
	s_setprio 1
	s_waitcnt lgkmcnt(0)
	v_mfma_f32_16x16x32_bf16 v[94:97], v[130:133], v[168:171], v[94:97]
	v_mfma_f32_16x16x32_bf16 v[90:93], v[138:141], v[168:171], v[90:93]
	v_mfma_f32_16x16x32_bf16 v[86:89], v[130:133], v[182:185], v[86:89]
	v_mfma_f32_16x16x32_bf16 v[82:85], v[138:141], v[182:185], v[82:85]
	v_mfma_f32_16x16x32_bf16 v[78:81], v[130:133], v[190:193], v[78:81]
	v_mfma_f32_16x16x32_bf16 v[74:77], v[138:141], v[190:193], v[74:77]
	v_mfma_f32_16x16x32_bf16 v[70:73], v[130:133], v[198:201], v[70:73]
	v_mfma_f32_16x16x32_bf16 v[66:69], v[138:141], v[198:201], v[66:69]
	v_mfma_f32_16x16x32_bf16 v[94:97], v[134:137], v[172:175], v[94:97]
	v_mfma_f32_16x16x32_bf16 v[90:93], v[142:145], v[172:175], v[90:93]
	v_mfma_f32_16x16x32_bf16 v[86:89], v[134:137], v[186:189], v[86:89]
	v_mfma_f32_16x16x32_bf16 v[82:85], v[142:145], v[186:189], v[82:85]
	v_mfma_f32_16x16x32_bf16 v[78:81], v[134:137], v[194:197], v[78:81]
	v_mfma_f32_16x16x32_bf16 v[74:77], v[142:145], v[194:197], v[74:77]
	v_mfma_f32_16x16x32_bf16 v[70:73], v[134:137], v[202:205], v[70:73]
	v_mfma_f32_16x16x32_bf16 v[66:69], v[142:145], v[202:205], v[66:69]
	v_mfma_f32_16x16x32_bf16 v[30:33], v[146:149], v[168:171], v[30:33]
	v_mfma_f32_16x16x32_bf16 v[26:29], v[154:157], v[168:171], v[26:29]
	v_mfma_f32_16x16x32_bf16 v[22:25], v[146:149], v[182:185], v[22:25]
	v_mfma_f32_16x16x32_bf16 v[18:21], v[154:157], v[182:185], v[18:21]
	v_mfma_f32_16x16x32_bf16 v[14:17], v[146:149], v[190:193], v[14:17]
	v_mfma_f32_16x16x32_bf16 v[10:13], v[154:157], v[190:193], v[10:13]
	v_mfma_f32_16x16x32_bf16 v[6:9], v[146:149], v[198:201], v[6:9]
	v_mfma_f32_16x16x32_bf16 v[2:5], v[154:157], v[198:201], v[2:5]
	v_mfma_f32_16x16x32_bf16 v[30:33], v[150:153], v[172:175], v[30:33]
	v_mfma_f32_16x16x32_bf16 v[26:29], v[158:161], v[172:175], v[26:29]
	v_mfma_f32_16x16x32_bf16 v[22:25], v[150:153], v[186:189], v[22:25]
	v_mfma_f32_16x16x32_bf16 v[18:21], v[158:161], v[186:189], v[18:21]
	v_mfma_f32_16x16x32_bf16 v[14:17], v[150:153], v[194:197], v[14:17]
	v_mfma_f32_16x16x32_bf16 v[10:13], v[158:161], v[194:197], v[10:13]
	v_mfma_f32_16x16x32_bf16 v[6:9], v[150:153], v[202:205], v[6:9]
	v_mfma_f32_16x16x32_bf16 v[2:5], v[158:161], v[202:205], v[2:5]
	s_setprio 0
	s_barrier
	s_add_i32 s47, s47, 2
	s_add_u32 s0, s0, 0x10000
	s_addc_u32 s1, s1, 0
	s_add_u32 s45, s45, 0x10000
	s_addc_u32 s46, s46, 0
	s_cmp_gt_u32 s47, 29
	s_cbranch_scc0 .LBB0_932
	s_and_b64 vcc, exec, s[10:11]
	s_cbranch_vccz .LBB0_935
	s_barrier
